# P4/P6: eight (not six) residual pieces read behind the exchange's first wait; K-loop exit waits vmcnt(8)
# speedup vs baseline: 1.0039x; 1.0023x over previous
.LBB0_572:
	s_waitcnt vmcnt(8)
	s_cmpk_gt_u32 s47, 0xff
	s_cbranch_scc1 .LBB0_574
	s_barrier
.LBB0_574:
	s_lshl_b32 s0, s15, 5
	s_lshl_b32 s6, s16, 8
	s_or_b32 s0, s6, s0
	s_lshl_b32 s40, s14, 8
	v_and_or_b32 v210, v150, 24, s0
	s_add_i32 s0, s40, s61
	v_or_b32_e32 v130, s0, v219
	v_ashrrev_i32_e32 v211, 31, v210
	v_ashrrev_i32_e32 v131, 31, v130
	v_lshl_add_u64 v[132:133], v[210:211], 1, s[38:39]
	v_lshlrev_b64 v[134:135], 11, v[130:131]
	v_lshl_add_u64 v[134:135], v[132:133], 0, v[134:135]
	s_barrier
	v_lshlrev_b32_e32 v234, 4, v1
	v_add_u32_e32 v234, s49, v234
	v_add_u32_e32 v235, 0x10000, v234
	ds_read_b128 v[194:197], v235 offset:0
	ds_read_b128 v[186:189], v235 offset:8192
	v_or_b32_e32 v134, 16, v130
	v_ashrrev_i32_e32 v135, 31, v134
	v_lshlrev_b64 v[134:135], 11, v[134:135]
	v_lshl_add_u64 v[134:135], v[132:133], 0, v[134:135]
	ds_read_b128 v[182:185], v235 offset:16384
	ds_read_b128 v[178:181], v235 offset:24576
	v_or_b32_e32 v134, 32, v130
	v_ashrrev_i32_e32 v135, 31, v134
	v_lshlrev_b64 v[134:135], 11, v[134:135]
	v_lshl_add_u64 v[134:135], v[132:133], 0, v[134:135]
	ds_read_b128 v[174:177], v234 offset:0
	ds_read_b128 v[170:173], v234 offset:8192
	v_or_b32_e32 v134, 48, v130
	v_ashrrev_i32_e32 v135, 31, v134
	v_lshlrev_b64 v[134:135], 11, v[134:135]
	v_lshl_add_u64 v[134:135], v[132:133], 0, v[134:135]
	v_add_u32_e32 v134, 0x80, v130
	v_ashrrev_i32_e32 v135, 31, v134
	v_lshlrev_b64 v[134:135], 11, v[134:135]
	v_lshl_add_u64 v[134:135], v[132:133], 0, v[134:135]
	v_add_u32_e32 v134, 0x90, v130
	v_ashrrev_i32_e32 v135, 31, v134
	v_lshlrev_b64 v[134:135], 11, v[134:135]
	v_lshl_add_u64 v[134:135], v[132:133], 0, v[134:135]
	v_add_u32_e32 v134, 0xa0, v130
	v_add_u32_e32 v130, 0xb0, v130
	v_ashrrev_i32_e32 v135, 31, v134
	v_ashrrev_i32_e32 v131, 31, v130
	v_lshlrev_b64 v[134:135], 11, v[134:135]
	v_lshlrev_b64 v[130:131], 11, v[130:131]
	v_lshl_add_u64 v[134:135], v[132:133], 0, v[134:135]
	v_lshl_add_u64 v[130:131], v[132:133], 0, v[130:131]
	s_nop 0
	global_load_dwordx4 v[134:137], v[130:131], off
	s_nop 0
	global_load_dwordx4 v[130:133], v[130:131], off offset:256
	s_waitcnt lgkmcnt(0)
	s_barrier
	v_mbcnt_lo_u32_b32 v190, -1, 0
	v_mbcnt_hi_u32_b32 v190, -1, v190
	v_and_b32_e32 v192, 64, v190
	v_xor_b32_e32 v191, 16, v190
	v_add_u32_e32 v192, 64, v192
	v_cmp_lt_i32_e32 vcc, v191, v192
	v_mul_f32_e32 v193, v129, v129
	v_fmac_f32_e32 v193, v128, v128
	v_cndmask_b32_e32 v191, v190, v191, vcc
	v_lshlrev_b32_e32 v220, 2, v191
	v_mul_f32_e32 v191, v127, v127
	v_fmac_f32_e32 v191, v126, v126
	v_add_f32_e32 v191, v191, v193
	v_mul_f32_e32 v193, v123, v123
	v_mul_f32_e32 v198, v125, v125
	v_fmac_f32_e32 v193, v122, v122
	v_fmac_f32_e32 v198, v124, v124
	v_add_f32_e32 v193, v193, v198
	v_add_f32_e32 v191, v193, v191
	v_mul_f32_e32 v193, v119, v119
	v_mul_f32_e32 v198, v121, v121
	v_fmac_f32_e32 v193, v118, v118
	v_fmac_f32_e32 v198, v120, v120
	v_add_f32_e32 v193, v193, v198
	v_add_f32_e32 v191, v193, v191
	v_mul_f32_e32 v193, v115, v115
	v_mul_f32_e32 v198, v117, v117
	v_fmac_f32_e32 v193, v114, v114
	v_fmac_f32_e32 v198, v116, v116
	v_add_f32_e32 v193, v193, v198
	v_add_f32_e32 v191, v193, v191
	v_mov_b32_e32 v193, v191
	s_nop 1
	v_permlane16_swap_b32_e32 v191, v193
	v_xor_b32_e32 v198, 32, v190
	v_cmp_lt_i32_e32 vcc, v198, v192
	s_lshl_b32 s0, s15, 2
	v_cmp_gt_u32_e64 s[6:7], 16, v1
	v_cndmask_b32_e32 v190, v190, v198, vcc
	v_lshlrev_b32_e32 v221, 2, v190
	s_waitcnt lgkmcnt(0)
	v_add_f32_e32 v190, v191, v193
	v_mov_b32_e32 v191, v190
	s_nop 1
	v_permlane32_swap_b32_e32 v190, v191
	s_add_i32 s15, s0, 0
	s_and_saveexec_b64 s[8:9], s[6:7]
	s_cbranch_execz .LBB0_576
	s_lshl_b32 s0, s1, 10
	s_add_i32 s0, s15, s0
	v_lshl_add_u32 v192, v219, 4, s0
	s_waitcnt lgkmcnt(0)
	v_add_f32_e32 v190, v190, v191
	ds_write_b32 v192, v190

.LBB0_592:
	s_or_b64 exec, exec, s[10:11]
	s_waitcnt vmcnt(0)
	ds_read_b128 v[166:169], v234 offset:16384
	ds_read_b128 v[162:165], v234 offset:24576
	ds_read_b128 v[158:161], v235 offset:32768
	ds_read_b128 v[154:157], v235 offset:40960
	ds_read_b128 v[150:153], v235 offset:49152
	ds_read_b128 v[146:149], v235 offset:57344
	ds_read_b128 v[142:145], v234 offset:32768
	ds_read_b128 v[138:141], v234 offset:40960
	s_add_u32 s0, s34, 0x10000
	s_addc_u32 s17, s35, 0
	v_cmp_eq_u32_e64 s[10:11], 0, v1
	s_and_saveexec_b64 s[18:19], s[10:11]
	s_cbranch_execz .LBB0_595
	s_mov_b64 s[20:21], exec
	v_mbcnt_lo_u32_b32 v190, s20, 0
	v_mbcnt_hi_u32_b32 v190, s21, v190
	v_cmp_eq_u32_e32 vcc, 0, v190
	s_and_b64 s[26:27], exec, vcc
	s_mov_b64 exec, s[26:27]
	s_cbranch_execz .LBB0_595
	s_lshl_b32 s26, s14, 6
	s_ashr_i32 s27, s26, 31
	s_lshl_b64 s[26:27], s[26:27], 2
	s_add_u32 s26, s0, s26
	s_addc_u32 s27, s17, s27
	s_bcnt1_i32_b64 s20, s[20:21]
	v_mov_b32_e32 v190, 0
	s_waitcnt lgkmcnt(0)
	v_mov_b32_e32 v191, s20
	global_atomic_add v190, v191, s[26:27]

.LBB0_879:
	s_waitcnt vmcnt(8)
	s_cmpk_gt_u32 s33, 0xff
	s_cbranch_scc1 .LBB0_881
	s_barrier
.LBB0_881:
	v_lshrrev_b32_e32 v214, 4, v1
	s_lshl_b32 s6, s10, 8
	s_lshl_b32 s2, s29, 8
	s_lshl_b32 s18, s31, 5
	v_lshl_or_b32 v130, v214, 3, s6
	s_add_i32 s4, s2, s30
	v_or_b32_e32 v178, s18, v130
	v_or_b32_e32 v130, s4, v213
	v_ashrrev_i32_e32 v179, 31, v178
	v_ashrrev_i32_e32 v131, 31, v130
	v_lshl_add_u64 v[132:133], v[178:179], 1, s[22:23]
	v_lshlrev_b64 v[134:135], 11, v[130:131]
	v_lshl_add_u64 v[134:135], v[132:133], 0, v[134:135]
	s_barrier
	v_lshlrev_b32_e32 v234, 4, v1
	v_add_u32_e32 v234, s36, v234
	v_add_u32_e32 v235, 0x10000, v234
	ds_read_b128 v[206:209], v235 offset:0
	ds_read_b128 v[202:205], v235 offset:8192
	v_or_b32_e32 v134, 16, v130
	v_ashrrev_i32_e32 v135, 31, v134
	v_lshlrev_b64 v[134:135], 11, v[134:135]
	v_lshl_add_u64 v[134:135], v[132:133], 0, v[134:135]
	ds_read_b128 v[198:201], v235 offset:16384
	ds_read_b128 v[186:189], v235 offset:24576
	v_or_b32_e32 v134, 32, v130
	v_ashrrev_i32_e32 v135, 31, v134
	v_lshlrev_b64 v[134:135], 11, v[134:135]
	v_lshl_add_u64 v[134:135], v[132:133], 0, v[134:135]
	ds_read_b128 v[174:177], v234 offset:0
	ds_read_b128 v[170:173], v234 offset:8192
	v_or_b32_e32 v134, 48, v130
	v_ashrrev_i32_e32 v135, 31, v134
	v_lshlrev_b64 v[134:135], 11, v[134:135]
	v_lshl_add_u64 v[134:135], v[132:133], 0, v[134:135]
	v_add_u32_e32 v134, 0x80, v130
	v_ashrrev_i32_e32 v135, 31, v134
	v_lshlrev_b64 v[134:135], 11, v[134:135]
	v_lshl_add_u64 v[134:135], v[132:133], 0, v[134:135]
	v_add_u32_e32 v134, 0x90, v130
	v_ashrrev_i32_e32 v135, 31, v134
	v_lshlrev_b64 v[134:135], 11, v[134:135]
	v_lshl_add_u64 v[134:135], v[132:133], 0, v[134:135]
	v_add_u32_e32 v134, 0xa0, v130
	v_add_u32_e32 v130, 0xb0, v130
	v_ashrrev_i32_e32 v135, 31, v134
	v_ashrrev_i32_e32 v131, 31, v130
	v_lshlrev_b64 v[134:135], 11, v[134:135]
	v_lshlrev_b64 v[130:131], 11, v[130:131]
	v_lshl_add_u64 v[134:135], v[132:133], 0, v[134:135]
	v_lshl_add_u64 v[130:131], v[132:133], 0, v[130:131]
	s_nop 0
	global_load_dwordx4 v[134:137], v[130:131], off
	s_nop 0
	global_load_dwordx4 v[130:133], v[130:131], off offset:256
	s_waitcnt lgkmcnt(0)
	s_barrier
	v_mul_f32_e32 v183, v127, v127
	v_mul_f32_e32 v184, v129, v129
	v_fmac_f32_e32 v183, v126, v126
	v_fmac_f32_e32 v184, v128, v128
	v_add_f32_e32 v183, v183, v184
	v_mul_f32_e32 v184, v123, v123
	v_mul_f32_e32 v185, v125, v125
	v_fmac_f32_e32 v184, v122, v122
	v_fmac_f32_e32 v185, v124, v124
	v_add_f32_e32 v184, v184, v185
	v_mbcnt_lo_u32_b32 v180, -1, 0
	v_add_f32_e32 v183, v184, v183
	v_mul_f32_e32 v184, v119, v119
	v_mul_f32_e32 v185, v121, v121
	v_mbcnt_hi_u32_b32 v181, -1, v180
	v_fmac_f32_e32 v184, v118, v118
	v_fmac_f32_e32 v185, v120, v120
	v_and_b32_e32 v182, 64, v181
	v_add_f32_e32 v184, v184, v185
	v_xor_b32_e32 v180, 16, v181
	v_add_u32_e32 v182, 64, v182
	v_add_f32_e32 v183, v184, v183
	v_mul_f32_e32 v184, v115, v115
	v_mul_f32_e32 v185, v117, v117
	v_cmp_lt_i32_e32 vcc, v180, v182
	v_fmac_f32_e32 v184, v114, v114
	v_fmac_f32_e32 v185, v116, v116
	v_cndmask_b32_e32 v180, v181, v180, vcc
	v_add_f32_e32 v184, v184, v185
	v_lshlrev_b32_e32 v180, 2, v180
	v_add_f32_e32 v183, v184, v183
	v_mov_b32_e32 v184, v183
	s_nop 1
	v_permlane16_swap_b32_e32 v183, v184
	v_xor_b32_e32 v185, 32, v181
	v_cmp_lt_i32_e32 vcc, v185, v182
	s_lshl_b32 s0, s31, 2
	s_add_i32 s3, s0, 0
	v_cndmask_b32_e32 v181, v181, v185, vcc
	v_lshlrev_b32_e32 v181, 2, v181
	s_waitcnt lgkmcnt(0)
	v_add_f32_e32 v182, v183, v184
	v_mov_b32_e32 v183, v182
	s_nop 1
	v_permlane32_swap_b32_e32 v182, v183
	v_cmp_gt_u32_e32 vcc, 16, v1
	s_and_saveexec_b64 s[0:1], vcc
	s_cbranch_execz .LBB0_883
	s_lshl_b32 s5, s11, 10
	s_add_i32 s5, s3, s5
	v_lshl_add_u32 v184, v213, 4, s5
	s_waitcnt lgkmcnt(0)
	v_add_f32_e32 v182, v182, v183
	ds_write_b32 v184, v182

.LBB0_899:
	s_or_b64 exec, exec, s[2:3]
	s_waitcnt vmcnt(0)
	ds_read_b128 v[166:169], v234 offset:16384
	ds_read_b128 v[162:165], v234 offset:24576
	ds_read_b128 v[158:161], v235 offset:32768
	ds_read_b128 v[154:157], v235 offset:40960
	ds_read_b128 v[150:153], v235 offset:49152
	ds_read_b128 v[146:149], v235 offset:57344
	ds_read_b128 v[142:145], v234 offset:32768
	ds_read_b128 v[138:141], v234 offset:40960
	s_add_u32 s5, s34, 0x20000
	s_addc_u32 s7, s35, 0
	v_cmp_eq_u32_e64 s[2:3], 0, v1
	s_and_saveexec_b64 s[10:11], s[2:3]
	s_cbranch_execz .LBB0_902
	s_mov_b64 s[12:13], exec
	v_mbcnt_lo_u32_b32 v182, s12, 0
	v_mbcnt_hi_u32_b32 v182, s13, v182
	v_cmp_eq_u32_e32 vcc, 0, v182
	s_and_b64 s[14:15], exec, vcc
	s_mov_b64 exec, s[14:15]
	s_cbranch_execz .LBB0_902
	s_lshl_b32 s14, s29, 6
	s_ashr_i32 s15, s14, 31
	s_lshl_b64 s[14:15], s[14:15], 2
	s_add_u32 s14, s5, s14
	s_addc_u32 s15, s7, s15
	s_bcnt1_i32_b64 s12, s[12:13]
	v_mov_b32_e32 v182, 0
	v_mov_b32_e32 v183, s12
	global_atomic_add v182, v183, s[14:15]
